# grid barrier poll loops without s_sleep (on v73)
# speedup vs baseline: 1.0048x; 1.0000x over previous
; __device__ __forceinline__ unsigned xb_ld(unsigned* p)              { return __hip_atomic_load(p, __ATOMIC_RELAXED, __HIP_MEMORY_SCOPE_AGENT); }
; __device__ __forceinline__ void xcd_barrier_complete(unsigned* bar, unsigned x, unsigned& nloc, unsigned& nx) {
;     ...
;     for (;;) {
;         sum = 0u; cnt = 0u; mine = 0u;
; #pragma unroll
;         for (unsigned j = 0; j < 16; ++j) { const unsigned c = xb_ld(&bar[XB_XCNT(j)]); sum += c; cnt += (c > 0u) ? 1u : 0u; mine = (j == x) ? c : mine; }
;         if (sum == G) break;
;         __builtin_amdgcn_s_sleep(1);
;         if ((++sp & 255u) == 0u) { if (xb_ld(&bar[XB_TMO])) break; if (sp > XB_SPIN_CAP) { atomicAdd(&bar[XB_TMO], 1u); break; } }
;     }
.Lg0_172:
	global_load_dword v15, v16, s[8:9] sc1
	s_waitcnt lgkmcnt(0)
	global_load_dword v0, v16, s[10:11] sc1
	global_load_dword v1, v16, s[12:13] sc1
	global_load_dword v2, v16, s[14:15] sc1
	global_load_dword v3, v16, s[16:17] sc1
	global_load_dword v4, v16, s[18:19] sc1
	global_load_dword v5, v16, s[20:21] sc1
	global_load_dword v6, v16, s[22:23] sc1
	global_load_dword v7, v16, s[24:25] sc1
	global_load_dword v8, v16, s[26:27] sc1
	global_load_dword v9, v16, s[28:29] sc1
	global_load_dword v10, v16, s[30:31] sc1
	global_load_dword v11, v16, s[34:35] sc1
	global_load_dword v12, v16, s[36:37] sc1
	global_load_dword v13, v16, s[38:39] sc1
	global_load_dword v14, v16, s[40:41] sc1
	s_mov_b64 s[52:53], -1
	s_mov_b64 s[54:55], -1
	s_waitcnt vmcnt(14)
	v_add_u32_e32 v17, v0, v15
	s_waitcnt vmcnt(13)
	v_add_u32_e32 v17, v17, v1
	s_waitcnt vmcnt(12)
	v_add_u32_e32 v17, v17, v2
	s_waitcnt vmcnt(11)
	v_add_u32_e32 v17, v17, v3
	s_waitcnt vmcnt(10)
	v_add_u32_e32 v17, v17, v4
	s_waitcnt vmcnt(9)
	v_add_u32_e32 v17, v17, v5
	s_waitcnt vmcnt(8)
	v_add_u32_e32 v17, v17, v6
	s_waitcnt vmcnt(7)
	v_add_u32_e32 v17, v17, v7
	s_waitcnt vmcnt(6)
	v_add_u32_e32 v17, v17, v8
	s_waitcnt vmcnt(5)
	v_add_u32_e32 v17, v17, v9
	s_waitcnt vmcnt(4)
	v_add_u32_e32 v17, v17, v10
	s_waitcnt vmcnt(3)
	v_add_u32_e32 v17, v17, v11
	s_waitcnt vmcnt(2)
	v_add_u32_e32 v17, v17, v12
	s_waitcnt vmcnt(1)
	v_add_u32_e32 v17, v17, v13
	s_waitcnt vmcnt(0)
	v_add_u32_e32 v17, v17, v14
	v_cmp_eq_u32_e32 vcc, s90, v17
	s_cbranch_vccnz .Lg0_171
	s_and_b32 s3, s1, 0xff
	s_cmp_eq_u32 s3, 0
	s_mov_b64 s[56:57], -1
	s_cbranch_scc0 .Lg0_176
	global_load_dword v17, v16, s[6:7] sc1
	s_waitcnt vmcnt(0)
	v_cmp_eq_u32_e32 vcc, 0, v17
	s_cbranch_vccnz .Lg0_178
	s_mov_b64 s[56:57], 0

.Lg0_190:
	s_and_b32 s1, s0, 0xff
	s_mov_b64 s[20:21], -1
	s_cmp_lg_u32 s1, 0
	s_mov_b64 s[24:25], -1
	s_cbranch_scc1 .Lg0_193
	global_load_dword v2, v0, s[6:7] sc1
	s_waitcnt vmcnt(0)
	v_cmp_eq_u32_e32 vcc, 0, v2
	s_cbranch_vccnz .Lg0_195
	s_mov_b64 s[24:25], 0
	s_mov_b64 s[22:23], -1

.Lg0_207:
	s_and_b32 s1, s0, 0xff
	s_cmp_lg_u32 s1, 0
	s_mov_b64 s[22:23], -1
	s_cbranch_scc1 .Lg0_210
	global_load_dword v1, v0, s[6:7] sc1
	s_waitcnt vmcnt(0)
	v_cmp_eq_u32_e32 vcc, 0, v1
	s_cbranch_vccnz .Lg0_212
	s_mov_b64 s[22:23], 0
	s_mov_b64 s[20:21], -1

; __device__ __forceinline__ unsigned xb_ld(unsigned* p)              { return __hip_atomic_load(p, __ATOMIC_RELAXED, __HIP_MEMORY_SCOPE_AGENT); }
; __device__ __forceinline__ void xcd_barrier_complete(unsigned* bar, unsigned x, unsigned& nloc, unsigned& nx) {
;     ...
;     for (;;) {
;         sum = 0u; cnt = 0u; mine = 0u;
; #pragma unroll
;         for (unsigned j = 0; j < 16; ++j) { const unsigned c = xb_ld(&bar[XB_XCNT(j)]); sum += c; cnt += (c > 0u) ? 1u : 0u; mine = (j == x) ? c : mine; }
;         if (sum == G) break;
;         __builtin_amdgcn_s_sleep(1);
;         if ((++sp & 255u) == 0u) { if (xb_ld(&bar[XB_TMO])) break; if (sp > XB_SPIN_CAP) { atomicAdd(&bar[XB_TMO], 1u); break; } }
;     }
.LBB0_245:
	global_load_dword v15, v16, s[8:9] sc1
	s_waitcnt lgkmcnt(0)
	global_load_dword v0, v16, s[10:11] sc1
	global_load_dword v1, v16, s[12:13] sc1
	global_load_dword v2, v16, s[14:15] sc1
	global_load_dword v3, v16, s[16:17] sc1
	global_load_dword v4, v16, s[18:19] sc1
	global_load_dword v5, v16, s[20:21] sc1
	global_load_dword v6, v16, s[22:23] sc1
	global_load_dword v7, v16, s[24:25] sc1
	global_load_dword v8, v16, s[26:27] sc1
	global_load_dword v9, v16, s[28:29] sc1
	global_load_dword v10, v16, s[30:31] sc1
	global_load_dword v11, v16, s[34:35] sc1
	global_load_dword v12, v16, s[36:37] sc1
	global_load_dword v13, v16, s[38:39] sc1
	global_load_dword v14, v16, s[40:41] sc1
	s_mov_b64 s[54:55], -1
	s_mov_b64 s[56:57], -1
	s_waitcnt vmcnt(14)
	v_add_u32_e32 v17, v0, v15
	s_waitcnt vmcnt(13)
	v_add_u32_e32 v17, v17, v1
	s_waitcnt vmcnt(12)
	v_add_u32_e32 v17, v17, v2
	s_waitcnt vmcnt(11)
	v_add_u32_e32 v17, v17, v3
	s_waitcnt vmcnt(10)
	v_add_u32_e32 v17, v17, v4
	s_waitcnt vmcnt(9)
	v_add_u32_e32 v17, v17, v5
	s_waitcnt vmcnt(8)
	v_add_u32_e32 v17, v17, v6
	s_waitcnt vmcnt(7)
	v_add_u32_e32 v17, v17, v7
	s_waitcnt vmcnt(6)
	v_add_u32_e32 v17, v17, v8
	s_waitcnt vmcnt(5)
	v_add_u32_e32 v17, v17, v9
	s_waitcnt vmcnt(4)
	v_add_u32_e32 v17, v17, v10
	s_waitcnt vmcnt(3)
	v_add_u32_e32 v17, v17, v11
	s_waitcnt vmcnt(2)
	v_add_u32_e32 v17, v17, v12
	s_waitcnt vmcnt(1)
	v_add_u32_e32 v17, v17, v13
	s_waitcnt vmcnt(0)
	v_add_u32_e32 v17, v17, v14
	v_cmp_eq_u32_e32 vcc, s90, v17
	s_cbranch_vccnz .LBB0_244
	s_and_b32 s3, s1, 0xff
	s_cmp_eq_u32 s3, 0
	s_mov_b64 s[58:59], -1
	s_cbranch_scc0 .LBB0_249
	global_load_dword v17, v16, s[6:7] sc1
	s_waitcnt vmcnt(0)
	v_cmp_eq_u32_e32 vcc, 0, v17
	s_cbranch_vccnz .LBB0_251
	s_mov_b64 s[58:59], 0

; __device__ __forceinline__ unsigned xb_ld(unsigned* p)              { return __hip_atomic_load(p, __ATOMIC_RELAXED, __HIP_MEMORY_SCOPE_AGENT); }
; __device__ __forceinline__ void xcd_barrier_complete(unsigned* bar, unsigned x, unsigned& nloc, unsigned& nx) {
;     ...
;     for (;;) {
;         sum = 0u; cnt = 0u; mine = 0u;
; #pragma unroll
;         for (unsigned j = 0; j < 16; ++j) { const unsigned c = xb_ld(&bar[XB_XCNT(j)]); sum += c; cnt += (c > 0u) ? 1u : 0u; mine = (j == x) ? c : mine; }
;         if (sum == G) break;
;         __builtin_amdgcn_s_sleep(1);
;         if ((++sp & 255u) == 0u) { if (xb_ld(&bar[XB_TMO])) break; if (sp > XB_SPIN_CAP) { atomicAdd(&bar[XB_TMO], 1u); break; } }
;     }
.LBB0_715:
	global_load_dword v15, v16, s[8:9] sc1
	s_waitcnt lgkmcnt(0)
	global_load_dword v0, v16, s[10:11] sc1
	global_load_dword v1, v16, s[12:13] sc1
	global_load_dword v2, v16, s[14:15] sc1
	global_load_dword v3, v16, s[16:17] sc1
	global_load_dword v4, v16, s[18:19] sc1
	global_load_dword v5, v16, s[20:21] sc1
	global_load_dword v6, v16, s[22:23] sc1
	global_load_dword v7, v16, s[24:25] sc1
	global_load_dword v8, v16, s[26:27] sc1
	global_load_dword v9, v16, s[28:29] sc1
	global_load_dword v10, v16, s[30:31] sc1
	global_load_dword v11, v16, s[34:35] sc1
	global_load_dword v12, v16, s[36:37] sc1
	global_load_dword v13, v16, s[38:39] sc1
	global_load_dword v14, v16, s[40:41] sc1
	s_mov_b64 s[56:57], -1
	s_mov_b64 s[58:59], -1
	s_waitcnt vmcnt(14)
	v_add_u32_e32 v17, v0, v15
	s_waitcnt vmcnt(13)
	v_add_u32_e32 v17, v17, v1
	s_waitcnt vmcnt(12)
	v_add_u32_e32 v17, v17, v2
	s_waitcnt vmcnt(11)
	v_add_u32_e32 v17, v17, v3
	s_waitcnt vmcnt(10)
	v_add_u32_e32 v17, v17, v4
	s_waitcnt vmcnt(9)
	v_add_u32_e32 v17, v17, v5
	s_waitcnt vmcnt(8)
	v_add_u32_e32 v17, v17, v6
	s_waitcnt vmcnt(7)
	v_add_u32_e32 v17, v17, v7
	s_waitcnt vmcnt(6)
	v_add_u32_e32 v17, v17, v8
	s_waitcnt vmcnt(5)
	v_add_u32_e32 v17, v17, v9
	s_waitcnt vmcnt(4)
	v_add_u32_e32 v17, v17, v10
	s_waitcnt vmcnt(3)
	v_add_u32_e32 v17, v17, v11
	s_waitcnt vmcnt(2)
	v_add_u32_e32 v17, v17, v12
	s_waitcnt vmcnt(1)
	v_add_u32_e32 v17, v17, v13
	s_waitcnt vmcnt(0)
	v_add_u32_e32 v17, v17, v14
	v_cmp_eq_u32_e32 vcc, s90, v17
	s_cbranch_vccnz .LBB0_714
	s_and_b32 s3, s1, 0xff
	s_cmp_eq_u32 s3, 0
	s_mov_b64 s[60:61], -1
	s_cbranch_scc0 .LBB0_719
	global_load_dword v17, v16, s[6:7] sc1
	s_waitcnt vmcnt(0)
	v_cmp_eq_u32_e32 vcc, 0, v17
	s_cbranch_vccnz .LBB0_721
	s_mov_b64 s[60:61], 0

; __device__ __forceinline__ unsigned xb_ld(unsigned* p)              { return __hip_atomic_load(p, __ATOMIC_RELAXED, __HIP_MEMORY_SCOPE_AGENT); }
; __device__ __forceinline__ void xcd_barrier_complete(unsigned* bar, unsigned x, unsigned& nloc, unsigned& nx) {
;     ...
;     for (;;) {
;         sum = 0u; cnt = 0u; mine = 0u;
; #pragma unroll
;         for (unsigned j = 0; j < 16; ++j) { const unsigned c = xb_ld(&bar[XB_XCNT(j)]); sum += c; cnt += (c > 0u) ? 1u : 0u; mine = (j == x) ? c : mine; }
;         if (sum == G) break;
;         __builtin_amdgcn_s_sleep(1);
;         if ((++sp & 255u) == 0u) { if (xb_ld(&bar[XB_TMO])) break; if (sp > XB_SPIN_CAP) { atomicAdd(&bar[XB_TMO], 1u); break; } }
;     }
.LBB0_1710:
	global_load_dword v15, v16, s[8:9] sc1
	s_waitcnt lgkmcnt(0)
	global_load_dword v0, v16, s[10:11] sc1
	global_load_dword v1, v16, s[12:13] sc1
	global_load_dword v2, v16, s[14:15] sc1
	global_load_dword v3, v16, s[16:17] sc1
	global_load_dword v4, v16, s[18:19] sc1
	global_load_dword v5, v16, s[20:21] sc1
	global_load_dword v6, v16, s[22:23] sc1
	global_load_dword v7, v16, s[24:25] sc1
	global_load_dword v8, v16, s[26:27] sc1
	global_load_dword v9, v16, s[28:29] sc1
	global_load_dword v10, v16, s[30:31] sc1
	global_load_dword v11, v16, s[34:35] sc1
	global_load_dword v12, v16, s[36:37] sc1
	global_load_dword v13, v16, s[38:39] sc1
	global_load_dword v14, v16, s[40:41] sc1
	s_mov_b64 s[52:53], -1
	s_mov_b64 s[56:57], -1
	s_waitcnt vmcnt(14)
	v_add_u32_e32 v17, v0, v15
	s_waitcnt vmcnt(13)
	v_add_u32_e32 v17, v17, v1
	s_waitcnt vmcnt(12)
	v_add_u32_e32 v17, v17, v2
	s_waitcnt vmcnt(11)
	v_add_u32_e32 v17, v17, v3
	s_waitcnt vmcnt(10)
	v_add_u32_e32 v17, v17, v4
	s_waitcnt vmcnt(9)
	v_add_u32_e32 v17, v17, v5
	s_waitcnt vmcnt(8)
	v_add_u32_e32 v17, v17, v6
	s_waitcnt vmcnt(7)
	v_add_u32_e32 v17, v17, v7
	s_waitcnt vmcnt(6)
	v_add_u32_e32 v17, v17, v8
	s_waitcnt vmcnt(5)
	v_add_u32_e32 v17, v17, v9
	s_waitcnt vmcnt(4)
	v_add_u32_e32 v17, v17, v10
	s_waitcnt vmcnt(3)
	v_add_u32_e32 v17, v17, v11
	s_waitcnt vmcnt(2)
	v_add_u32_e32 v17, v17, v12
	s_waitcnt vmcnt(1)
	v_add_u32_e32 v17, v17, v13
	s_waitcnt vmcnt(0)
	v_add_u32_e32 v17, v17, v14
	v_cmp_eq_u32_e32 vcc, s90, v17
	s_cbranch_vccnz .LBB0_1709
	s_and_b32 s3, s1, 0xff
	s_cmp_eq_u32 s3, 0
	s_mov_b64 s[58:59], -1
	s_cbranch_scc0 .LBB0_1714
	global_load_dword v17, v16, s[6:7] sc1
	s_waitcnt vmcnt(0)
	v_cmp_eq_u32_e32 vcc, 0, v17
	s_cbranch_vccnz .LBB0_1716
	s_mov_b64 s[58:59], 0

; __device__ __forceinline__ unsigned xb_ld(unsigned* p)              { return __hip_atomic_load(p, __ATOMIC_RELAXED, __HIP_MEMORY_SCOPE_AGENT); }
; __device__ __forceinline__ void xcd_barrier_complete(unsigned* bar, unsigned x, unsigned& nloc, unsigned& nx) {
;     ...
;     for (;;) {
;         sum = 0u; cnt = 0u; mine = 0u;
; #pragma unroll
;         for (unsigned j = 0; j < 16; ++j) { const unsigned c = xb_ld(&bar[XB_XCNT(j)]); sum += c; cnt += (c > 0u) ? 1u : 0u; mine = (j == x) ? c : mine; }
;         if (sum == G) break;
;         __builtin_amdgcn_s_sleep(1);
;         if ((++sp & 255u) == 0u) { if (xb_ld(&bar[XB_TMO])) break; if (sp > XB_SPIN_CAP) { atomicAdd(&bar[XB_TMO], 1u); break; } }
;     }
.LBB0_1770:
	global_load_dword v15, v16, s[4:5] sc1
	s_waitcnt lgkmcnt(0)
	global_load_dword v0, v16, s[6:7] sc1
	global_load_dword v1, v16, s[8:9] sc1
	global_load_dword v2, v16, s[10:11] sc1
	global_load_dword v3, v16, s[12:13] sc1
	global_load_dword v4, v16, s[14:15] sc1
	global_load_dword v5, v16, s[16:17] sc1
	global_load_dword v6, v16, s[18:19] sc1
	global_load_dword v7, v16, s[20:21] sc1
	global_load_dword v8, v16, s[22:23] sc1
	global_load_dword v9, v16, s[24:25] sc1
	global_load_dword v10, v16, s[26:27] sc1
	global_load_dword v11, v16, s[28:29] sc1
	global_load_dword v12, v16, s[30:31] sc1
	global_load_dword v13, v16, s[34:35] sc1
	global_load_dword v14, v16, s[36:37] sc1
	s_mov_b64 s[38:39], -1
	s_mov_b64 s[40:41], -1
	s_waitcnt vmcnt(14)
	v_add_u32_e32 v17, v0, v15
	s_waitcnt vmcnt(13)
	v_add_u32_e32 v17, v17, v1
	s_waitcnt vmcnt(12)
	v_add_u32_e32 v17, v17, v2
	s_waitcnt vmcnt(11)
	v_add_u32_e32 v17, v17, v3
	s_waitcnt vmcnt(10)
	v_add_u32_e32 v17, v17, v4
	s_waitcnt vmcnt(9)
	v_add_u32_e32 v17, v17, v5
	s_waitcnt vmcnt(8)
	v_add_u32_e32 v17, v17, v6
	s_waitcnt vmcnt(7)
	v_add_u32_e32 v17, v17, v7
	s_waitcnt vmcnt(6)
	v_add_u32_e32 v17, v17, v8
	s_waitcnt vmcnt(5)
	v_add_u32_e32 v17, v17, v9
	s_waitcnt vmcnt(4)
	v_add_u32_e32 v17, v17, v10
	s_waitcnt vmcnt(3)
	v_add_u32_e32 v17, v17, v11
	s_waitcnt vmcnt(2)
	v_add_u32_e32 v17, v17, v12
	s_waitcnt vmcnt(1)
	v_add_u32_e32 v17, v17, v13
	s_waitcnt vmcnt(0)
	v_add_u32_e32 v17, v17, v14
	v_cmp_eq_u32_e32 vcc, s90, v17
	s_cbranch_vccnz .LBB0_1769
	s_and_b32 s38, s42, 0xff
	s_cmp_eq_u32 s38, 0
	s_mov_b64 s[38:39], -1
	s_mov_b64 s[44:45], -1
	s_cbranch_scc0 .LBB0_1774
	global_load_dword v17, v16, s[2:3] sc1
	s_waitcnt vmcnt(0)
	v_cmp_eq_u32_e32 vcc, 0, v17
	s_cbranch_vccnz .LBB0_1776
	s_mov_b64 s[44:45], 0

.LBB0_1788:
	s_and_b32 s18, s22, 0xff
	s_mov_b64 s[16:17], -1
	s_cmp_lg_u32 s18, 0
	s_mov_b64 s[20:21], -1
	s_cbranch_scc1 .LBB0_1791
	global_load_dword v2, v0, s[2:3] sc1
	s_waitcnt vmcnt(0)
	v_cmp_eq_u32_e32 vcc, 0, v2
	s_cbranch_vccnz .LBB0_1793
	s_mov_b64 s[20:21], 0
	s_mov_b64 s[18:19], -1

.LBB0_1805:
	s_and_b32 s16, s22, 0xff
	s_cmp_lg_u32 s16, 0
	s_mov_b64 s[18:19], -1
	s_cbranch_scc1 .LBB0_1808
	global_load_dword v1, v0, s[2:3] sc1
	s_waitcnt vmcnt(0)
	v_cmp_eq_u32_e32 vcc, 0, v1
	s_cbranch_vccnz .LBB0_1810
	s_mov_b64 s[18:19], 0
	s_mov_b64 s[16:17], -1
